# partial last round of in-proj/up GEMMs as 128-row half tiles on all CUs, with a K-loop that stages and multiplies only the needed A half
# speedup vs baseline: 1.0175x; 1.0016x over previous
; template <class Epi, class Sched, bool ALIGN_EPI = false, bool SP2 = false>
; __device__ __forceinline__ void gemm_phase(PG8_LAS unsigned char* lds, const Gemm g, const Sched& S, const Epi& E, const int tid_in) {
;     ...
;         const char* nA = has_next ? (const char*)g.A + (size_t)nxt.pm * tstep : cA; const char* nB = has_next ? (const char*)g.Bt + (size_t)nxt.pn * tstep : cB;
;         for (int t = 0; t < nt; t += 2) {
;             const bool last = (t == nt - 2);
;             const char* a1 = cA + (size_t)(t + 1) * kstep;
;             const char* a2 = last ? nA : cA + (size_t)(t + 2) * kstep; const char* b2 = last ? nB : cB + (size_t)(t + 2) * kstep;
;             const char* a3 = a2 + kstep; const char* b3 = b2 + kstep;
;     ...
; #pragma unroll
;         for (int a = 0; a < 2; ++a)
; #pragma unroll
;             for (int b = 0; b < 2; ++b)
; #pragma unroll
;                 for (int m = 0; m < 4; ++m)
; #pragma unroll
;                     for (int n = 0; n < 2; ++n) acc[a][b][m][n] = (f32x4){0.f, 0.f, 0.f, 0.f};
.LBB0_373:
	s_ashr_i32 s57, s56, 31
	s_lshl_b64 s[4:5], s[56:57], 20
	s_add_u32 s58, s90, s4
	s_addc_u32 s59, s91, s5
	s_lshr_b32 s4, s101, 1
	s_lshl_b32 s4, s4, 19
	s_add_u32 s58, s58, s4
	s_addc_u32 s59, s59, 0
	s_and_b64 s[4:5], s[36:37], exec
	s_cselect_b32 s1, s59, s31
	s_cselect_b32 s4, s58, s30
	s_ashr_i32 s55, s54, 31
	s_lshl_b64 s[6:7], s[54:55], 20
	s_add_u32 s60, s67, s6
	s_addc_u32 s61, s68, s7
	s_and_b64 s[6:7], s[36:37], exec
	s_cselect_b32 s5, s61, s63
	s_cselect_b32 s6, s60, s62
	s_add_u32 s30, s30, 0x80080
	s_addc_u32 s31, s31, 0
	s_add_u32 s7, s62, 0x100
	v_mov_b32_e32 v0, 0
	s_addc_u32 s8, s63, 0
	s_mov_b32 s9, -2
	v_mov_b32_e32 v1, v0
	v_mov_b32_e32 v2, v0
	v_mov_b32_e32 v3, v0
	v_mov_b32_e32 v4, v0
	v_mov_b32_e32 v5, v0
	v_mov_b32_e32 v6, v0
	v_mov_b32_e32 v7, v0
	v_mov_b32_e32 v16, v0
	v_mov_b32_e32 v17, v0
	v_mov_b32_e32 v18, v0
	v_mov_b32_e32 v19, v0
	v_mov_b32_e32 v20, v0
	v_mov_b32_e32 v21, v0
	v_mov_b32_e32 v22, v0
	v_mov_b32_e32 v23, v0
	v_mov_b32_e32 v32, v0
	v_mov_b32_e32 v33, v0
	v_mov_b32_e32 v34, v0
	v_mov_b32_e32 v35, v0
	v_mov_b32_e32 v36, v0
	v_mov_b32_e32 v37, v0
	v_mov_b32_e32 v38, v0
	v_mov_b32_e32 v39, v0
	v_mov_b32_e32 v48, v0
	v_mov_b32_e32 v49, v0
	v_mov_b32_e32 v50, v0
	v_mov_b32_e32 v51, v0
	v_mov_b32_e32 v52, v0
	v_mov_b32_e32 v53, v0
	v_mov_b32_e32 v54, v0
	v_mov_b32_e32 v55, v0
	v_mov_b32_e32 v8, v0
	v_mov_b32_e32 v9, v0
	v_mov_b32_e32 v10, v0
	v_mov_b32_e32 v11, v0
	v_mov_b32_e32 v12, v0
	v_mov_b32_e32 v13, v0
	v_mov_b32_e32 v14, v0
	v_mov_b32_e32 v15, v0
	v_mov_b32_e32 v24, v0
	v_mov_b32_e32 v25, v0
	v_mov_b32_e32 v26, v0
	v_mov_b32_e32 v27, v0
	v_mov_b32_e32 v28, v0
	v_mov_b32_e32 v29, v0
	v_mov_b32_e32 v30, v0
	v_mov_b32_e32 v31, v0
	v_mov_b32_e32 v40, v0
	v_mov_b32_e32 v41, v0
	v_mov_b32_e32 v42, v0
	v_mov_b32_e32 v43, v0
	v_mov_b32_e32 v44, v0
	v_mov_b32_e32 v45, v0
	v_mov_b32_e32 v46, v0
	v_mov_b32_e32 v47, v0
	v_mov_b32_e32 v56, v0
	v_mov_b32_e32 v57, v0
	v_mov_b32_e32 v58, v0
	v_mov_b32_e32 v59, v0
	v_mov_b32_e32 v60, v0
	v_mov_b32_e32 v61, v0
	v_mov_b32_e32 v62, v0
	v_mov_b32_e32 v63, v0
	v_mov_b32_e32 v64, v0
	v_mov_b32_e32 v65, v0
	v_mov_b32_e32 v66, v0
	v_mov_b32_e32 v67, v0
	v_mov_b32_e32 v68, v0
	v_mov_b32_e32 v69, v0
	v_mov_b32_e32 v70, v0
	v_mov_b32_e32 v71, v0
	s_waitcnt vmcnt(0)
	v_mov_b32_e32 v80, v0
	v_mov_b32_e32 v81, v0
	v_mov_b32_e32 v82, v0
	v_mov_b32_e32 v83, v0
	v_mov_b32_e32 v86, v0
	v_mov_b32_e32 v87, v0
	v_mov_b32_e32 v88, v0
	v_mov_b32_e32 v89, v0
	v_mov_b32_e32 v98, v0
	v_mov_b32_e32 v99, v0
	v_mov_b32_e32 v100, v0
	v_mov_b32_e32 v101, v0
	v_mov_b32_e32 v102, v0
	v_mov_b32_e32 v103, v0
	v_mov_b32_e32 v104, v0
	v_mov_b32_e32 v105, v0
	v_mov_b32_e32 v114, v0
	v_mov_b32_e32 v115, v0
	v_mov_b32_e32 v116, v0
	v_mov_b32_e32 v117, v0
	v_mov_b32_e32 v118, v0
	v_mov_b32_e32 v119, v0
	v_mov_b32_e32 v120, v0
	v_mov_b32_e32 v121, v0
	v_mov_b32_e32 v72, v0
	v_mov_b32_e32 v73, v0
	v_mov_b32_e32 v74, v0
	v_mov_b32_e32 v75, v0
	v_mov_b32_e32 v76, v0
	v_mov_b32_e32 v77, v0
	v_mov_b32_e32 v78, v0
	v_mov_b32_e32 v79, v0
	v_mov_b32_e32 v90, v0
	v_mov_b32_e32 v91, v0
	v_mov_b32_e32 v92, v0
	v_mov_b32_e32 v93, v0
	v_mov_b32_e32 v94, v0
	v_mov_b32_e32 v95, v0
	v_mov_b32_e32 v96, v0
	v_mov_b32_e32 v97, v0
	v_mov_b32_e32 v106, v0
	v_mov_b32_e32 v107, v0
	v_mov_b32_e32 v108, v0
	v_mov_b32_e32 v109, v0
	v_mov_b32_e32 v110, v0
	v_mov_b32_e32 v111, v0
	v_mov_b32_e32 v112, v0
	v_mov_b32_e32 v113, v0
	v_mov_b32_e32 v122, v0
	v_mov_b32_e32 v123, v0
	v_mov_b32_e32 v124, v0
	v_mov_b32_e32 v125, v0
	v_mov_b32_e32 v126, v0
	v_mov_b32_e32 v127, v0
	v_mov_b32_e32 v128, v0
	v_mov_b32_e32 v129, v0
	s_bitcmp1_b32 s100, 0
	s_cbranch_scc1 .Lhl_loop

; #define PG8_MMA(ai, bj, At, Bt) do { __builtin_amdgcn_s_setprio(1); _Pragma("unroll") for (int m = 0; m < 4; ++m) _Pragma("unroll") for (int n = 0; n < 2; ++n) _Pragma("unroll") for (int k = 0; k < 2; ++k) \
;         acc[ai][bj][m][n] = __builtin_amdgcn_mfma_f32_16x16x32_bf16(Bt[n][k], At[m][k], acc[ai][bj][m][n], 0, 0, 0); __builtin_amdgcn_s_setprio(0); } while (0)
; #define PG8_WAIT_V(n) asm volatile("s_waitcnt vmcnt(" #n ")" ::: "memory")
; #define PG8_WAIT_L(n) asm volatile("s_waitcnt lgkmcnt(" #n ")" ::: "memory")
; #define PG8_BAR __builtin_amdgcn_s_barrier()
; #define PG8_SCHED __builtin_amdgcn_sched_barrier(0)
; template <class Epi, class Sched, bool ALIGN_EPI = false, bool SP2 = false>
; __device__ __forceinline__ void gemm_phase(PG8_LAS unsigned char* lds, const Gemm g, const Sched& S, const Epi& E, const int tid_in) {
;     ...
;             PG8_WAIT_V(8); PG8_WAIT_L(0); PG8_BAR; PG8_MMA(1, 0, At, B0); PG8_MMA(1, 1, At, B1); PG8_BAR; PG8_SCHED;
;     ...
;         if constexpr (ALIGN_EPI) { if (wr == 0) PG8_BAR; }
.Lht_skip_b:
	s_barrier
	s_add_i32 s9, s9, 2
	s_add_u32 s30, s30, 0x100
	s_addc_u32 s31, s31, 0
	s_add_u32 s7, s7, 0x100
	s_addc_u32 s8, s8, 0
	s_cmp_gt_u32 s9, 29
	s_cbranch_scc0 .LBB0_374
.Lhl_done:
	s_and_b64 vcc, exec, s[48:49]
	s_cbranch_vccz .LBB0_377
	s_barrier

; #define PG8_STAGE(bufoff, gbase, voff) do { _Pragma("unroll") for (int _i = 0; _i < 2; ++_i) \
;         __builtin_amdgcn_global_load_lds((const unsigned*)((const char*)(gbase) + (voff)[_i]), (PG8_LAS unsigned*)(lds + (bufoff) + ldsw + _i * 8192), 16, 0, 0); } while (0)
; #define PG8_LDA(dst, b, h) do { _Pragma("unroll") for (int m = 0; m < 4; ++m) _Pragma("unroll") for (int k = 0; k < 2; ++k) dst[m][k] = *(const PG8_LAS bf16x8*)(lds + PG8_SA(b, h) + aoff + m * 2048 + k * 1024); } while (0)
; #define PG8_LDB(dst, b, h) do { _Pragma("unroll") for (int n = 0; n < 2; ++n) _Pragma("unroll") for (int k = 0; k < 2; ++k) dst[n][k] = *(const PG8_LAS bf16x8*)(lds + PG8_SB(b, h) + boff + n * 2048 + k * 1024); } while (0)
; #define PG8_MMA(ai, bj, At, Bt) do { __builtin_amdgcn_s_setprio(1); _Pragma("unroll") for (int m = 0; m < 4; ++m) _Pragma("unroll") for (int n = 0; n < 2; ++n) _Pragma("unroll") for (int k = 0; k < 2; ++k) \
;         acc[ai][bj][m][n] = __builtin_amdgcn_mfma_f32_16x16x32_bf16(Bt[n][k], At[m][k], acc[ai][bj][m][n], 0, 0, 0); __builtin_amdgcn_s_setprio(0); } while (0)
; #define PG8_WAIT_V(n) asm volatile("s_waitcnt vmcnt(" #n ")" ::: "memory")
; #define PG8_WAIT_L(n) asm volatile("s_waitcnt lgkmcnt(" #n ")" ::: "memory")
; #define PG8_BAR __builtin_amdgcn_s_barrier()
; #define PG8_SCHED __builtin_amdgcn_sched_barrier(0)
; template <class Epi, class Sched, bool ALIGN_EPI = false, bool SP2 = false>
; __device__ __forceinline__ void gemm_phase(PG8_LAS unsigned char* lds, const Gemm g, const Sched& S, const Epi& E, const int tid_in) {
;     ...
;             PG8_LDB(B0, 0, 0); PG8_LDB(B1, 0, 1); PG8_SCHED; PG8_LDA(At, 0, 0); PG8_STAGE(PG8_SA(1, 1), a1 + hstep, voffA);
;             PG8_WAIT_V(8); PG8_WAIT_L(0); PG8_BAR; PG8_MMA(0, 0, At, B0); PG8_MMA(0, 1, At, B1); PG8_BAR; PG8_SCHED;
;             PG8_LDA(At, 0, 1); PG8_STAGE(PG8_SB(0, 0), b2, voffB); PG8_STAGE(PG8_SB(0, 1), b2 + hstep, voffB); PG8_STAGE(PG8_SA(0, 0), a2, voffA);
;             PG8_WAIT_V(8); PG8_WAIT_L(0); PG8_BAR; PG8_MMA(1, 0, At, B0); PG8_MMA(1, 1, At, B1); PG8_BAR; PG8_SCHED;
.Lhl_loop:
	s_add_u32 s10, s30, 0xfff80080
	s_addc_u32 s11, s31, -1
	s_add_i32 s12, 0, 0x10000
	s_cmp_eq_u32 s9, 28
	s_cselect_b32 s65, s1, s11
	s_cselect_b32 s64, s4, s10
	s_cselect_b32 s63, s5, s8
	s_cselect_b32 s62, s6, s7
	s_add_i32 s13, 0, 0x14000
	v_add_u32_e32 v142, s12, v196
	v_add_u32_e32 v158, s13, v196
	ds_read_b128 v[130:133], v142
	ds_read_b128 v[134:137], v142 offset:1024
	ds_read_b128 v[138:141], v142 offset:2048
	ds_read_b128 v[142:145], v142 offset:3072
	ds_read_b128 v[146:149], v158
	ds_read_b128 v[150:153], v158 offset:1024
	ds_read_b128 v[154:157], v158 offset:2048
	ds_read_b128 v[158:161], v158 offset:3072
	ds_read_b128 v[162:165], v199
	ds_read_b128 v[166:169], v199 offset:1024
	ds_read_b128 v[170:173], v199 offset:2048
	ds_read_b128 v[190:193], v199 offset:3072
	ds_read_b128 v[202:205], v199 offset:4096
	ds_read_b128 v[224:227], v199 offset:5120
	ds_read_b128 v[228:231], v199 offset:6144
	ds_read_b128 v[232:235], v199 offset:7168
	s_waitcnt vmcnt(6)
	s_waitcnt lgkmcnt(0)
	s_barrier
	s_setprio 1
	s_waitcnt lgkmcnt(0)
	v_mfma_f32_16x16x32_bf16 v[126:129], v[130:133], v[162:165], v[126:129]
	v_mfma_f32_16x16x32_bf16 v[122:125], v[138:141], v[162:165], v[122:125]
	v_mfma_f32_16x16x32_bf16 v[110:113], v[130:133], v[170:173], v[110:113]
	v_mfma_f32_16x16x32_bf16 v[106:109], v[138:141], v[170:173], v[106:109]
	v_mfma_f32_16x16x32_bf16 v[94:97], v[130:133], v[202:205], v[94:97]
	v_mfma_f32_16x16x32_bf16 v[90:93], v[138:141], v[202:205], v[90:93]
	v_mfma_f32_16x16x32_bf16 v[76:79], v[130:133], v[228:231], v[76:79]
	v_mfma_f32_16x16x32_bf16 v[72:75], v[138:141], v[228:231], v[72:75]
	v_mfma_f32_16x16x32_bf16 v[126:129], v[134:137], v[166:169], v[126:129]
	v_mfma_f32_16x16x32_bf16 v[122:125], v[142:145], v[166:169], v[122:125]
	v_mfma_f32_16x16x32_bf16 v[110:113], v[134:137], v[190:193], v[110:113]
	v_mfma_f32_16x16x32_bf16 v[106:109], v[142:145], v[190:193], v[106:109]
	v_mfma_f32_16x16x32_bf16 v[94:97], v[134:137], v[224:227], v[94:97]
	v_mfma_f32_16x16x32_bf16 v[90:93], v[142:145], v[224:227], v[90:93]
	v_mfma_f32_16x16x32_bf16 v[76:79], v[134:137], v[232:235], v[76:79]
	v_mfma_f32_16x16x32_bf16 v[72:75], v[142:145], v[232:235], v[72:75]
	s_setprio 0
	s_setprio 1
	v_mfma_f32_16x16x32_bf16 v[118:121], v[146:149], v[162:165], v[118:121]
	v_mfma_f32_16x16x32_bf16 v[114:117], v[154:157], v[162:165], v[114:117]
	v_mfma_f32_16x16x32_bf16 v[102:105], v[146:149], v[170:173], v[102:105]
	v_mfma_f32_16x16x32_bf16 v[98:101], v[154:157], v[170:173], v[98:101]
	v_mfma_f32_16x16x32_bf16 v[86:89], v[146:149], v[202:205], v[86:89]
	v_mfma_f32_16x16x32_bf16 v[80:83], v[154:157], v[202:205], v[80:83]
	v_mfma_f32_16x16x32_bf16 v[68:71], v[146:149], v[228:231], v[68:71]
	v_mfma_f32_16x16x32_bf16 v[64:67], v[154:157], v[228:231], v[64:67]
	v_mfma_f32_16x16x32_bf16 v[118:121], v[150:153], v[166:169], v[118:121]
	v_mfma_f32_16x16x32_bf16 v[114:117], v[158:161], v[166:169], v[114:117]
	v_mfma_f32_16x16x32_bf16 v[102:105], v[150:153], v[190:193], v[102:105]
	v_mfma_f32_16x16x32_bf16 v[98:101], v[158:161], v[190:193], v[98:101]
	v_mfma_f32_16x16x32_bf16 v[86:89], v[150:153], v[224:227], v[86:89]
	v_mfma_f32_16x16x32_bf16 v[80:83], v[158:161], v[224:227], v[80:83]
	v_mfma_f32_16x16x32_bf16 v[68:71], v[150:153], v[232:235], v[68:71]
	v_mfma_f32_16x16x32_bf16 v[64:67], v[158:161], v[232:235], v[64:67]
	s_setprio 0
	s_barrier
	s_add_i32 s10, s12, s66
	v_lshl_add_u64 v[194:195], s[62:63], 0, v[84:85]
	s_mov_b32 m0, s10
	global_load_lds_dwordx4 v[194:195], off
	s_add_i32 m0, s10, 0x2000
	s_add_u32 s10, s62, 0x80000
	v_lshl_add_u64 v[236:237], s[62:63], 0, v[178:179]
	s_addc_u32 s11, s63, 0
	s_add_i32 s12, s13, s66
	global_load_lds_dwordx4 v[236:237], off
	v_lshl_add_u64 v[238:239], s[10:11], 0, v[84:85]
	s_mov_b32 m0, s12
	v_lshl_add_u64 v[240:241], s[64:65], 0, v[176:177]
	global_load_lds_dwordx4 v[238:239], off
	v_lshl_add_u64 v[238:239], s[10:11], 0, v[178:179]
	s_add_i32 m0, s12, 0x2000
	s_nop 0
	global_load_lds_dwordx4 v[238:239], off
	v_lshl_add_u64 v[238:239], s[64:65], 0, v[174:175]
	s_mov_b32 m0, s69
	s_nop 0
	global_load_lds_dwordx4 v[238:239], off
	s_mov_b32 m0, s70
	s_nop 0
	global_load_lds_dwordx4 v[240:241], off
	s_waitcnt vmcnt(6)
	s_waitcnt lgkmcnt(0)
	s_barrier
	s_barrier
; #define PG8_STAGE(bufoff, gbase, voff) do { _Pragma("unroll") for (int _i = 0; _i < 2; ++_i) \
;         __builtin_amdgcn_global_load_lds((const unsigned*)((const char*)(gbase) + (voff)[_i]), (PG8_LAS unsigned*)(lds + (bufoff) + ldsw + _i * 8192), 16, 0, 0); } while (0)
; #define PG8_LDA(dst, b, h) do { _Pragma("unroll") for (int m = 0; m < 4; ++m) _Pragma("unroll") for (int k = 0; k < 2; ++k) dst[m][k] = *(const PG8_LAS bf16x8*)(lds + PG8_SA(b, h) + aoff + m * 2048 + k * 1024); } while (0)
; #define PG8_LDB(dst, b, h) do { _Pragma("unroll") for (int n = 0; n < 2; ++n) _Pragma("unroll") for (int k = 0; k < 2; ++k) dst[n][k] = *(const PG8_LAS bf16x8*)(lds + PG8_SB(b, h) + boff + n * 2048 + k * 1024); } while (0)
; #define PG8_MMA(ai, bj, At, Bt) do { __builtin_amdgcn_s_setprio(1); _Pragma("unroll") for (int m = 0; m < 4; ++m) _Pragma("unroll") for (int n = 0; n < 2; ++n) _Pragma("unroll") for (int k = 0; k < 2; ++k) \
;         acc[ai][bj][m][n] = __builtin_amdgcn_mfma_f32_16x16x32_bf16(Bt[n][k], At[m][k], acc[ai][bj][m][n], 0, 0, 0); __builtin_amdgcn_s_setprio(0); } while (0)
; #define PG8_WAIT_V(n) asm volatile("s_waitcnt vmcnt(" #n ")" ::: "memory")
; #define PG8_WAIT_L(n) asm volatile("s_waitcnt lgkmcnt(" #n ")" ::: "memory")
; #define PG8_BAR __builtin_amdgcn_s_barrier()
; #define PG8_SCHED __builtin_amdgcn_sched_barrier(0)
; template <class Epi, class Sched, bool ALIGN_EPI = false, bool SP2 = false>
; __device__ __forceinline__ void gemm_phase(PG8_LAS unsigned char* lds, const Gemm g, const Sched& S, const Epi& E, const int tid_in) {
;     ...
;             PG8_LDB(B0, 1, 0); PG8_LDB(B1, 1, 1); PG8_SCHED; PG8_LDA(At, 1, 0); PG8_STAGE(PG8_SA(0, 1), a2 + hstep, voffA);
;             PG8_WAIT_V(8); PG8_WAIT_L(0); PG8_BAR; PG8_MMA(0, 0, At, B0); PG8_MMA(0, 1, At, B1); PG8_BAR; PG8_SCHED;
;             PG8_LDA(At, 1, 1); PG8_STAGE(PG8_SB(1, 0), b3, voffB); PG8_STAGE(PG8_SB(1, 1), b3 + hstep, voffB); PG8_STAGE(PG8_SA(1, 0), a3, voffA);
;             PG8_WAIT_V(8); PG8_WAIT_L(0); PG8_BAR; PG8_MMA(1, 0, At, B0); PG8_MMA(1, 1, At, B1); PG8_BAR; PG8_SCHED;
	s_add_i32 s12, 0, 0x18000
	s_add_i32 s13, 0, 0x1c000
	v_add_u32_e32 v142, s12, v196
	v_add_u32_e32 v158, s13, v196
	ds_read_b128 v[130:133], v142
	ds_read_b128 v[134:137], v142 offset:1024
	ds_read_b128 v[138:141], v142 offset:2048
	ds_read_b128 v[142:145], v142 offset:3072
	ds_read_b128 v[146:149], v158
	ds_read_b128 v[150:153], v158 offset:1024
	ds_read_b128 v[154:157], v158 offset:2048
	ds_read_b128 v[158:161], v158 offset:3072
	ds_read_b128 v[162:165], v199 offset:32768
	ds_read_b128 v[166:169], v199 offset:33792
	ds_read_b128 v[170:173], v199 offset:34816
	ds_read_b128 v[190:193], v199 offset:35840
	ds_read_b128 v[202:205], v199 offset:36864
	ds_read_b128 v[224:227], v199 offset:37888
	ds_read_b128 v[228:231], v199 offset:38912
	ds_read_b128 v[232:235], v199 offset:39936
	s_waitcnt vmcnt(6)
	s_waitcnt lgkmcnt(0)
	s_barrier
	s_setprio 1
	s_waitcnt lgkmcnt(0)
	v_mfma_f32_16x16x32_bf16 v[126:129], v[130:133], v[162:165], v[126:129]
	v_mfma_f32_16x16x32_bf16 v[122:125], v[138:141], v[162:165], v[122:125]
	v_mfma_f32_16x16x32_bf16 v[110:113], v[130:133], v[170:173], v[110:113]
	v_mfma_f32_16x16x32_bf16 v[106:109], v[138:141], v[170:173], v[106:109]
	v_mfma_f32_16x16x32_bf16 v[94:97], v[130:133], v[202:205], v[94:97]
	v_mfma_f32_16x16x32_bf16 v[90:93], v[138:141], v[202:205], v[90:93]
	v_mfma_f32_16x16x32_bf16 v[76:79], v[130:133], v[228:231], v[76:79]
	v_mfma_f32_16x16x32_bf16 v[72:75], v[138:141], v[228:231], v[72:75]
	v_mfma_f32_16x16x32_bf16 v[126:129], v[134:137], v[166:169], v[126:129]
	v_mfma_f32_16x16x32_bf16 v[122:125], v[142:145], v[166:169], v[122:125]
	v_mfma_f32_16x16x32_bf16 v[110:113], v[134:137], v[190:193], v[110:113]
	v_mfma_f32_16x16x32_bf16 v[106:109], v[142:145], v[190:193], v[106:109]
	v_mfma_f32_16x16x32_bf16 v[94:97], v[134:137], v[224:227], v[94:97]
	v_mfma_f32_16x16x32_bf16 v[90:93], v[142:145], v[224:227], v[90:93]
	v_mfma_f32_16x16x32_bf16 v[76:79], v[134:137], v[232:235], v[76:79]
	v_mfma_f32_16x16x32_bf16 v[72:75], v[142:145], v[232:235], v[72:75]
	s_setprio 0
	s_setprio 1
	v_mfma_f32_16x16x32_bf16 v[118:121], v[146:149], v[162:165], v[118:121]
	v_mfma_f32_16x16x32_bf16 v[114:117], v[154:157], v[162:165], v[114:117]
	v_mfma_f32_16x16x32_bf16 v[102:105], v[146:149], v[170:173], v[102:105]
	v_mfma_f32_16x16x32_bf16 v[98:101], v[154:157], v[170:173], v[98:101]
	v_mfma_f32_16x16x32_bf16 v[86:89], v[146:149], v[202:205], v[86:89]
	v_mfma_f32_16x16x32_bf16 v[80:83], v[154:157], v[202:205], v[80:83]
	v_mfma_f32_16x16x32_bf16 v[68:71], v[146:149], v[228:231], v[68:71]
	v_mfma_f32_16x16x32_bf16 v[64:67], v[154:157], v[228:231], v[64:67]
	v_mfma_f32_16x16x32_bf16 v[118:121], v[150:153], v[166:169], v[118:121]
	v_mfma_f32_16x16x32_bf16 v[114:117], v[158:161], v[166:169], v[114:117]
	v_mfma_f32_16x16x32_bf16 v[102:105], v[150:153], v[190:193], v[102:105]
	v_mfma_f32_16x16x32_bf16 v[98:101], v[158:161], v[190:193], v[98:101]
	v_mfma_f32_16x16x32_bf16 v[86:89], v[150:153], v[224:227], v[86:89]
	v_mfma_f32_16x16x32_bf16 v[80:83], v[158:161], v[224:227], v[80:83]
	v_mfma_f32_16x16x32_bf16 v[68:71], v[150:153], v[232:235], v[68:71]
	v_mfma_f32_16x16x32_bf16 v[64:67], v[158:161], v[232:235], v[64:67]
	s_setprio 0
	s_barrier
	s_add_i32 s10, s12, s66
	v_lshl_add_u64 v[194:195], v[194:195], 0, s[2:3]
	s_mov_b32 m0, s10
	global_load_lds_dwordx4 v[194:195], off
	s_add_i32 m0, s10, 0x2000
	s_add_u32 s10, s62, 0x80080
	v_lshl_add_u64 v[194:195], v[236:237], 0, s[2:3]
	s_addc_u32 s11, s63, 0
	s_add_i32 s12, s13, s66
	global_load_lds_dwordx4 v[194:195], off
	v_lshl_add_u64 v[194:195], s[10:11], 0, v[84:85]
	s_mov_b32 m0, s12
	s_nop 0
	global_load_lds_dwordx4 v[194:195], off
	v_lshl_add_u64 v[194:195], s[10:11], 0, v[178:179]
	s_add_i32 m0, s12, 0x2000
	s_nop 0
	global_load_lds_dwordx4 v[194:195], off
	v_lshl_add_u64 v[194:195], v[238:239], 0, s[2:3]
	s_mov_b32 m0, s74
	s_nop 0
	global_load_lds_dwordx4 v[194:195], off
	v_lshl_add_u64 v[194:195], v[240:241], 0, s[2:3]
	s_mov_b32 m0, s75
	s_nop 0
	global_load_lds_dwordx4 v[194:195], off
	s_waitcnt vmcnt(6)
	s_waitcnt lgkmcnt(0)
	s_barrier
	s_barrier
	s_add_i32 s9, s9, 2
	s_add_u32 s30, s30, 0x100
	s_addc_u32 s31, s31, 0
	s_add_u32 s7, s7, 0x100
	s_addc_u32 s8, s8, 0
	s_cmp_gt_u32 s9, 29
	s_cbranch_scc0 .Lhl_loop
	s_branch .Lhl_done
